# v26 + residual-GEMM epilogues (FFN-down, out-proj; both passes): LDS reads of the 16-step read/fma/store chain land in 4 rotating free quads and are issued 4 steps ahead (counted lgkmcnt) instead of r
# baseline (speedup 1.0000x reference)
.LBB0_132:
	s_load_dwordx2 s[30:31], s[30:31], 0x0
	s_ashr_i32 s21, s20, 31
	s_lshl_b64 s[20:21], s[20:21], 12
	v_mov_b32_e32 v201, v200
	s_waitcnt vmcnt(16)
	v_pk_mul_f32 v[14:15], v[200:201], v[194:195]
	s_waitcnt lgkmcnt(0)
	s_add_u32 s20, s30, s20
	s_addc_u32 s21, s31, s21
	v_ashrrev_i32_e32 v201, 2, v232
	s_add_u32 s20, s20, s46
	v_lshlrev_b32_e32 v0, 4, v0
	v_and_b32_e32 v194, -16, v201
	s_addc_u32 s21, s21, s47
	v_and_b32_e32 v0, 0x3f0, v0
	v_ashrrev_i32_e32 v195, 31, v194
	v_pk_mul_f32 v[204:205], v[202:203], v[192:193]
	v_lshl_add_u64 v[192:193], s[20:21], 0, v[0:1]
	v_lshlrev_b64 v[208:209], 12, v[194:195]
	v_mad_u64_u32 v[194:195], s[20:21], v194, s36, v[0:1]
	v_lshl_add_u64 v[192:193], v[192:193], 0, v[208:209]
	ds_read_b128 v[236:239], v194
	ds_read_b128 v[240:243], v194 offset:1040
	ds_read_b128 v[244:247], v194 offset:2080
	ds_read_b128 v[248:251], v194 offset:3120
	s_movk_i32 s4, 0x4000
	s_waitcnt vmcnt(3) lgkmcnt(3)
	v_pk_fma_f32 v[198:199], v[14:15], v[238:239], v[198:199]
	v_pk_fma_f32 v[196:197], v[204:205], v[236:237], v[196:197]
	global_store_dwordx4 v[192:193], v[196:199], off
	ds_read_b128 v[236:239], v194 offset:4160
	s_waitcnt lgkmcnt(3)
	v_pk_fma_f32 v[188:189], v[204:205], v[240:241], v[188:189]
	v_add_co_u32_e32 v196, vcc, s92, v192
	v_pk_fma_f32 v[190:191], v[14:15], v[242:243], v[190:191]
	s_nop 0
	v_addc_co_u32_e32 v197, vcc, 0, v193, vcc
	global_store_dwordx4 v[196:197], v[188:191], off offset:-4096
	ds_read_b128 v[240:243], v194 offset:5200
	s_waitcnt lgkmcnt(3)
	v_pk_fma_f32 v[186:187], v[14:15], v[246:247], v[186:187]
	v_pk_fma_f32 v[184:185], v[204:205], v[244:245], v[184:185]
	global_store_dwordx4 v[196:197], v[184:187], off
	ds_read_b128 v[244:247], v194 offset:6240
	s_waitcnt lgkmcnt(3)
	v_pk_fma_f32 v[180:181], v[204:205], v[248:249], v[180:181]
	v_add_co_u32_e32 v184, vcc, s4, v192
	v_pk_fma_f32 v[182:183], v[14:15], v[250:251], v[182:183]
	s_nop 0
	v_addc_co_u32_e32 v185, vcc, 0, v193, vcc
	global_store_dwordx4 v[184:185], v[180:183], off offset:-4096
	ds_read_b128 v[248:251], v194 offset:7280
	s_mov_b32 s4, 0x8000
	s_waitcnt lgkmcnt(3)
	v_pk_fma_f32 v[178:179], v[14:15], v[238:239], v[178:179]
	v_pk_fma_f32 v[176:177], v[204:205], v[236:237], v[176:177]
	global_store_dwordx4 v[184:185], v[176:179], off
	ds_read_b128 v[236:239], v194 offset:8320
	s_waitcnt lgkmcnt(3)
	v_pk_fma_f32 v[172:173], v[204:205], v[240:241], v[172:173]
	v_add_co_u32_e32 v176, vcc, s37, v192
	v_pk_fma_f32 v[174:175], v[14:15], v[242:243], v[174:175]
	s_nop 0
	v_addc_co_u32_e32 v177, vcc, 0, v193, vcc
	global_store_dwordx4 v[176:177], v[172:175], off offset:-4096
	ds_read_b128 v[240:243], v194 offset:9360
	s_waitcnt lgkmcnt(3)
	v_pk_fma_f32 v[170:171], v[14:15], v[246:247], v[170:171]
	v_pk_fma_f32 v[168:169], v[204:205], v[244:245], v[168:169]
	global_store_dwordx4 v[176:177], v[168:171], off
	ds_read_b128 v[244:247], v194 offset:10400
	s_waitcnt lgkmcnt(3)
	v_pk_fma_f32 v[164:165], v[204:205], v[248:249], v[164:165]
	v_add_co_u32_e32 v168, vcc, s4, v192
	v_pk_fma_f32 v[166:167], v[14:15], v[250:251], v[166:167]
	s_nop 0
	v_addc_co_u32_e32 v169, vcc, 0, v193, vcc
	global_store_dwordx4 v[168:169], v[164:167], off offset:-4096
	ds_read_b128 v[248:251], v194 offset:11440
	s_mov_b32 s4, 0xa000
	s_waitcnt lgkmcnt(3)
	v_pk_fma_f32 v[162:163], v[14:15], v[238:239], v[162:163]
	v_pk_fma_f32 v[160:161], v[204:205], v[236:237], v[160:161]
	global_store_dwordx4 v[168:169], v[160:163], off
	ds_read_b128 v[236:239], v194 offset:12480
	s_waitcnt lgkmcnt(3)
	v_pk_fma_f32 v[156:157], v[204:205], v[240:241], v[156:157]
	v_add_co_u32_e32 v160, vcc, s4, v192
	v_pk_fma_f32 v[158:159], v[14:15], v[242:243], v[158:159]
	s_nop 0
	v_addc_co_u32_e32 v161, vcc, 0, v193, vcc
	global_store_dwordx4 v[160:161], v[156:159], off offset:-4096
	ds_read_b128 v[240:243], v194 offset:13520
	s_mov_b32 s4, 0xe000
	s_waitcnt lgkmcnt(3)
	v_pk_fma_f32 v[154:155], v[14:15], v[246:247], v[154:155]
	v_pk_fma_f32 v[152:153], v[204:205], v[244:245], v[152:153]
	global_store_dwordx4 v[160:161], v[152:155], off
	ds_read_b128 v[244:247], v194 offset:14560
	s_waitcnt lgkmcnt(3)
	v_pk_fma_f32 v[148:149], v[204:205], v[248:249], v[148:149]
	v_add_co_u32_e32 v152, vcc, s39, v192
	v_pk_fma_f32 v[150:151], v[14:15], v[250:251], v[150:151]
	s_nop 0
	v_addc_co_u32_e32 v153, vcc, 0, v193, vcc
	global_store_dwordx4 v[152:153], v[148:151], off offset:-4096
	s_waitcnt lgkmcnt(2)
	v_pk_fma_f32 v[146:147], v[14:15], v[238:239], v[146:147]
	v_pk_fma_f32 v[144:145], v[204:205], v[236:237], v[144:145]
	global_store_dwordx4 v[152:153], v[144:147], off
	s_waitcnt vmcnt(15) lgkmcnt(1)
	v_pk_fma_f32 v[10:11], v[204:205], v[240:241], v[10:11]
	v_add_co_u32_e32 v144, vcc, s4, v192
	v_pk_fma_f32 v[12:13], v[14:15], v[242:243], v[12:13]
	s_nop 0
	v_addc_co_u32_e32 v145, vcc, 0, v193, vcc
	global_store_dwordx4 v[144:145], v[10:13], off offset:-4096
	s_mov_b32 s4, 0xf000
	s_waitcnt vmcnt(15) lgkmcnt(0)
	v_pk_fma_f32 v[8:9], v[14:15], v[246:247], v[8:9]
	v_pk_fma_f32 v[6:7], v[204:205], v[244:245], v[6:7]
	global_store_dwordx4 v[144:145], v[6:9], off
	s_nop 1
	v_or_b32_e32 v6, 15, v201
	v_mad_u64_u32 v[6:7], s[20:21], v6, s36, v[0:1]
	ds_read_b128 v[6:9], v6
	v_mov_b32_e32 v0, v206
	s_waitcnt vmcnt(15) lgkmcnt(0)
	v_pk_fma_f32 v[2:3], v[204:205], v[6:7], v[2:3]
	v_add_co_u32_e32 v6, vcc, s4, v192
	v_pk_fma_f32 v[4:5], v[14:15], v[8:9], v[4:5]
	s_nop 0
	v_addc_co_u32_e32 v7, vcc, 0, v193, vcc
	global_store_dwordx4 v[6:7], v[2:5], off
	s_mov_b32 s4, 0x81000
	v_lshlrev_b32_e32 v0, 4, v0
	v_mov_b32_e32 v4, v206
	v_and_b32_e32 v0, 0x3f0, v0
	v_lshl_add_u64 v[2:3], s[22:23], 0, v[0:1]
	v_ashrrev_i32_e32 v0, 2, v4
	v_and_b32_e32 v4, -16, v0
	v_ashrrev_i32_e32 v5, 31, v4
	v_lshlrev_b64 v[4:5], 12, v[4:5]
	v_lshl_add_u64 v[2:3], v[2:3], 0, v[4:5]
	v_add_co_u32_e32 v4, vcc, s4, v2
	s_mov_b32 s4, 0x83000
	s_nop 0
	v_addc_co_u32_e32 v5, vcc, 0, v3, vcc
	global_load_dwordx4 v[192:195], v[4:5], off offset:-4096
	global_load_dwordx4 v[188:191], v[4:5], off
	v_add_co_u32_e32 v4, vcc, s4, v2
	s_mov_b32 s4, 0x85000
	s_nop 0
	v_addc_co_u32_e32 v5, vcc, 0, v3, vcc
	global_load_dwordx4 v[184:187], v[4:5], off offset:-4096
	global_load_dwordx4 v[180:183], v[4:5], off
	v_add_co_u32_e32 v4, vcc, s4, v2
	s_mov_b32 s4, 0x87000
	s_nop 0
	v_addc_co_u32_e32 v5, vcc, 0, v3, vcc
	global_load_dwordx4 v[176:179], v[4:5], off offset:-4096
	global_load_dwordx4 v[172:175], v[4:5], off
	v_add_co_u32_e32 v4, vcc, s4, v2
	s_mov_b32 s4, 0x89000
	s_nop 0
	v_addc_co_u32_e32 v5, vcc, 0, v3, vcc
	global_load_dwordx4 v[168:171], v[4:5], off offset:-4096
	global_load_dwordx4 v[164:167], v[4:5], off
	v_add_co_u32_e32 v4, vcc, s4, v2
	s_mov_b32 s4, 0x8b000
	s_nop 0
	v_addc_co_u32_e32 v5, vcc, 0, v3, vcc
	global_load_dwordx4 v[160:163], v[4:5], off offset:-4096
	global_load_dwordx4 v[156:159], v[4:5], off
	v_add_co_u32_e32 v4, vcc, s4, v2
	s_mov_b32 s4, 0x8d000
	s_nop 0
	v_addc_co_u32_e32 v5, vcc, 0, v3, vcc
	global_load_dwordx4 v[152:155], v[4:5], off offset:-4096
	global_load_dwordx4 v[148:151], v[4:5], off
	v_add_co_u32_e32 v4, vcc, s4, v2
	s_nop 1
	v_addc_co_u32_e32 v5, vcc, 0, v3, vcc
	global_load_dwordx4 v[144:147], v[4:5], off offset:-4096
	global_load_dwordx4 v[10:13], v[4:5], off
	v_add_co_u32_e32 v4, vcc, 0x8e000, v2
	s_nop 1
	v_addc_co_u32_e32 v5, vcc, 0, v3, vcc
	v_add_co_u32_e32 v2, vcc, 0x8f000, v2
	global_load_dwordx4 v[6:9], v[4:5], off
	s_nop 0
	v_addc_co_u32_e32 v3, vcc, 0, v3, vcc
	global_load_dwordx4 v[2:5], v[2:3], off
	s_barrier
	s_and_saveexec_b64 s[20:21], s[42:43]
	s_cbranch_execz .LBB0_134
	v_lshlrev_b32_e32 v0, 2, v230
	v_lshl_add_u32 v196, v231, 2, v0
	ds_write2_b32 v196, v128, v112 offset1:32
	v_add_u32_e32 v112, 0x400, v196
	ds_write2_b32 v112, v129, v113 offset0:4 offset1:36
	v_add_u32_e32 v112, 0x800, v196
	ds_write2_b32 v112, v130, v114 offset0:8 offset1:40
	v_add_u32_e32 v112, 0xc00, v196
	ds_write2_b32 v112, v131, v115 offset0:12 offset1:44
	v_add_u32_e32 v112, 0x2000, v196
	ds_write2_b32 v112, v132, v116 offset0:32 offset1:64
	v_add_u32_e32 v112, 0x2400, v196
	ds_write2_b32 v112, v133, v117 offset0:36 offset1:68
	v_add_u32_e32 v112, 0x2800, v196
	ds_write2_b32 v112, v134, v118 offset0:40 offset1:72
	v_add_u32_e32 v112, 0x2c00, v196
	ds_write2_b32 v112, v135, v119 offset0:44 offset1:76
	v_add_u32_e32 v112, 0x4000, v196
	ds_write2_b32 v112, v136, v120 offset0:64 offset1:96
	v_add_u32_e32 v112, 0x4400, v196
	ds_write2_b32 v112, v137, v121 offset0:68 offset1:100
	v_add_u32_e32 v112, 0x4800, v196
	ds_write2_b32 v112, v138, v122 offset0:72 offset1:104
	v_add_u32_e32 v112, 0x4c00, v196
	ds_write2_b32 v112, v139, v123 offset0:76 offset1:108
	v_add_u32_e32 v112, 0x6000, v196
	ds_write2_b32 v112, v140, v124 offset0:96 offset1:128
	v_add_u32_e32 v112, 0x6400, v196
	ds_write2_b32 v112, v141, v125 offset0:100 offset1:132
	v_add_u32_e32 v112, 0x6800, v196
	ds_write2_b32 v112, v142, v126 offset0:104 offset1:136
	v_add_u32_e32 v112, 0x6c00, v196
	ds_write2_b32 v112, v143, v127 offset0:108 offset1:140
	v_add_u32_e32 v112, 0x8000, v196
	ds_write2_b32 v112, v96, v80 offset0:128 offset1:160
	v_add_u32_e32 v80, 0x8400, v196
	ds_write2_b32 v80, v97, v81 offset0:132 offset1:164
	v_add_u32_e32 v80, 0x8800, v196
	ds_write2_b32 v80, v98, v82 offset0:136 offset1:168
	v_add_u32_e32 v80, 0x8c00, v196
	ds_write2_b32 v80, v99, v83 offset0:140 offset1:172
	v_add_u32_e32 v80, 0xa000, v196
	ds_write2_b32 v80, v100, v84 offset0:160 offset1:192
	v_add_u32_e32 v80, 0xa400, v196
	ds_write2_b32 v80, v101, v85 offset0:164 offset1:196
	v_add_u32_e32 v80, 0xa800, v196
	ds_write2_b32 v80, v102, v86 offset0:168 offset1:200
	v_add_u32_e32 v80, 0xac00, v196
	ds_write2_b32 v80, v103, v87 offset0:172 offset1:204
	v_add_u32_e32 v80, 0xc000, v196
	ds_write2_b32 v80, v104, v88 offset0:192 offset1:224
	v_add_u32_e32 v80, 0xc400, v196
	ds_write2_b32 v80, v105, v89 offset0:196 offset1:228
	v_add_u32_e32 v80, 0xc800, v196
	ds_write2_b32 v80, v106, v90 offset0:200 offset1:232
	v_add_u32_e32 v80, 0xcc00, v196
	ds_write2_b32 v80, v107, v91 offset0:204 offset1:236
	v_add_u32_e32 v80, 0xe200, v196
	ds_write2_b32 v80, v108, v92 offset0:96 offset1:128
	v_add_u32_e32 v80, 0xe600, v196
	ds_write2_b32 v80, v109, v93 offset0:100 offset1:132
	v_add_u32_e32 v80, 0xea00, v196
	ds_write2_b32 v80, v110, v94 offset0:104 offset1:136
	v_add_u32_e32 v80, 0xee00, v196
	ds_write2_b32 v80, v111, v95 offset0:108 offset1:140
	v_add_u32_e32 v80, 0x10400, v196
	ds_write_b32 v80, v64
	v_add_u32_e32 v64, 0x10810, v196
	ds_write_b32 v64, v65
	v_add_u32_e32 v64, 0x10c20, v196
	ds_write_b32 v64, v66
	v_add_u32_e32 v64, 0x11030, v196
	ds_write_b32 v64, v67
	v_add_u32_e32 v64, 0x12480, v196
	ds_write_b32 v64, v68
	v_add_u32_e32 v64, 0x12890, v196
	ds_write_b32 v64, v69
	v_add_u32_e32 v64, 0x12ca0, v196
	ds_write_b32 v64, v70
	v_add_u32_e32 v64, 0x130b0, v196
	ds_write_b32 v64, v71
	v_add_u32_e32 v64, 0x14500, v196
	ds_write_b32 v64, v72
	v_add_u32_e32 v64, 0x14910, v196
	ds_write_b32 v64, v73
	v_add_u32_e32 v64, 0x14d20, v196
	ds_write_b32 v64, v74
	v_add_u32_e32 v64, 0x15130, v196
	ds_write_b32 v64, v75
	v_add_u32_e32 v64, 0x16580, v196
	ds_write_b32 v64, v76
	v_add_u32_e32 v64, 0x16990, v196
	ds_write_b32 v64, v77
	v_add_u32_e32 v64, 0x16da0, v196
	ds_write_b32 v64, v78
	v_add_u32_e32 v64, 0x171b0, v196
	ds_write_b32 v64, v79
	v_add_u32_e32 v64, 0x10480, v196
	ds_write_b32 v64, v48
	v_add_u32_e32 v48, 0x10890, v196
	ds_write_b32 v48, v49
	v_add_u32_e32 v48, 0x10ca0, v196
	ds_write_b32 v48, v50
	v_add_u32_e32 v48, 0x110b0, v196
	ds_write_b32 v48, v51
	v_add_u32_e32 v48, 0x12500, v196
	ds_write_b32 v48, v52
	v_add_u32_e32 v48, 0x12910, v196
	ds_write_b32 v48, v53
	v_add_u32_e32 v48, 0x12d20, v196
	ds_write_b32 v48, v54
	v_add_u32_e32 v48, 0x13130, v196
	ds_write_b32 v48, v55
	v_add_u32_e32 v48, 0x14580, v196
	ds_write_b32 v48, v56
	v_add_u32_e32 v48, 0x14990, v196
	ds_write_b32 v48, v57
	v_add_u32_e32 v48, 0x14da0, v196
	ds_write_b32 v48, v58
	v_add_u32_e32 v48, 0x151b0, v196
	ds_write_b32 v48, v59
	v_add_u32_e32 v48, 0x16600, v196
	ds_write_b32 v48, v60
	v_add_u32_e32 v48, 0x16a10, v196
	ds_write_b32 v48, v61
	v_add_u32_e32 v48, 0x16e20, v196
	ds_write_b32 v48, v62
	v_add_u32_e32 v48, 0x17230, v196
	ds_write_b32 v48, v63
	v_add_u32_e32 v48, 0x18600, v196
	ds_write_b32 v48, v32
	v_add_u32_e32 v32, 0x18a10, v196
	ds_write_b32 v32, v33
	v_add_u32_e32 v32, 0x18e20, v196
	ds_write_b32 v32, v34
	v_add_u32_e32 v32, 0x19230, v196
	ds_write_b32 v32, v35
	v_add_u32_e32 v32, 0x1a680, v196
	ds_write_b32 v32, v36
	v_add_u32_e32 v32, 0x1aa90, v196
	ds_write_b32 v32, v37
	v_add_u32_e32 v32, 0x1aea0, v196
	ds_write_b32 v32, v38
	v_add_u32_e32 v32, 0x1b2b0, v196
	ds_write_b32 v32, v39
	v_add_u32_e32 v32, 0x1c700, v196
	ds_write_b32 v32, v40
	v_add_u32_e32 v32, 0x1cb10, v196
	ds_write_b32 v32, v41
	v_add_u32_e32 v32, 0x1cf20, v196
	ds_write_b32 v32, v42
	v_add_u32_e32 v32, 0x1d330, v196
	ds_write_b32 v32, v43
	v_add_u32_e32 v32, 0x1e780, v196
	ds_write_b32 v32, v44
	v_add_u32_e32 v32, 0x1eb90, v196
	ds_write_b32 v32, v45
	v_add_u32_e32 v32, 0x1efa0, v196
	ds_write_b32 v32, v46
	v_mov_b32_e32 v32, 0x7b
	v_lshl_or_b32 v32, v229, 2, v32
	v_mad_u64_u32 v[32:33], s[22:23], v32, s36, v[0:1]
	v_add_u32_e32 v0, 0x18680, v196
	ds_write_b32 v32, v47
	ds_write_b32 v0, v16
	v_add_u32_e32 v0, 0x18a90, v196
	ds_write_b32 v0, v17
	v_add_u32_e32 v0, 0x18ea0, v196
	ds_write_b32 v0, v18
	v_add_u32_e32 v0, 0x192b0, v196
	ds_write_b32 v0, v19
	v_add_u32_e32 v0, 0x1a700, v196
	ds_write_b32 v0, v20
	v_add_u32_e32 v0, 0x1ab10, v196
	ds_write_b32 v0, v21
	v_add_u32_e32 v0, 0x1af20, v196
	ds_write_b32 v0, v22
	v_add_u32_e32 v0, 0x1b330, v196
	ds_write_b32 v0, v23
	v_add_u32_e32 v0, 0x1c780, v196
	ds_write_b32 v0, v24
	v_add_u32_e32 v0, 0x1cb90, v196
	ds_write_b32 v0, v25
	v_add_u32_e32 v0, 0x1cfa0, v196
	ds_write_b32 v0, v26
	v_add_u32_e32 v0, 0x1d3b0, v196
	ds_write_b32 v0, v27
	v_add_u32_e32 v0, 0x1e800, v196
	ds_write_b32 v0, v28
	v_add_u32_e32 v0, 0x1ec10, v196
	ds_write_b32 v0, v29
	v_add_u32_e32 v0, 0x1f020, v196
	ds_write_b32 v0, v30
	ds_write_b32 v32, v31 offset:128

.LBB0_138:
	s_load_dwordx2 s[22:23], s[22:23], 0x0
	s_ashr_i32 s21, s20, 31
	s_lshl_b64 s[20:21], s[20:21], 12
	v_ashrrev_i32_e32 v20, 2, v16
	v_lshlrev_b32_e32 v0, 4, v0
	s_waitcnt lgkmcnt(0)
	s_add_u32 s20, s22, s20
	s_addc_u32 s21, s23, s21
	s_add_u32 s20, s20, s46
	v_and_b32_e32 v22, -16, v20
	s_addc_u32 s21, s21, s47
	v_and_b32_e32 v0, 0x3f0, v0
	v_ashrrev_i32_e32 v23, 31, v22
	v_lshl_add_u64 v[18:19], s[20:21], 0, v[0:1]
	v_lshlrev_b64 v[16:17], 12, v[22:23]
	v_lshl_add_u64 v[16:17], v[18:19], 0, v[16:17]
	v_mad_u64_u32 v[18:19], s[20:21], v22, s36, v[0:1]
	ds_read_b128 v[236:239], v18
	ds_read_b128 v[240:243], v18 offset:1040
	ds_read_b128 v[244:247], v18 offset:2080
	ds_read_b128 v[248:251], v18 offset:3120
	s_mov_b32 s4, 0x81000
	v_add_co_u32_e32 v26, vcc, s4, v16
	s_mov_b32 s4, 0x83000
	s_waitcnt vmcnt(15) lgkmcnt(3)
	v_pk_fma_f32 v[238:239], v[14:15], v[238:239], v[194:195]
	v_pk_fma_f32 v[236:237], v[204:205], v[236:237], v[192:193]
	v_addc_co_u32_e32 v27, vcc, 0, v17, vcc
	global_store_dwordx4 v[26:27], v[236:239], off offset:-4096
	ds_read_b128 v[236:239], v18 offset:4160
	s_mov_b32 s20, 0x8e000
	s_cmp_eq_u32 s26, 0
	v_readlane_b32 s6, v254, 25
	v_readlane_b32 s7, v254, 37
	s_waitcnt vmcnt(15) lgkmcnt(3)
	v_pk_fma_f32 v[242:243], v[14:15], v[242:243], v[190:191]
	v_pk_fma_f32 v[240:241], v[204:205], v[240:241], v[188:189]
	global_store_dwordx4 v[26:27], v[240:243], off
	ds_read_b128 v[240:243], v18 offset:5200
	v_add_co_u32_e32 v26, vcc, s4, v16
	s_mov_b32 s4, 0x85000
	s_nop 0
	v_addc_co_u32_e32 v27, vcc, 0, v17, vcc
	s_waitcnt vmcnt(15) lgkmcnt(3)
	v_pk_fma_f32 v[246:247], v[14:15], v[246:247], v[186:187]
	v_pk_fma_f32 v[244:245], v[204:205], v[244:245], v[184:185]
	global_store_dwordx4 v[26:27], v[244:247], off offset:-4096
	ds_read_b128 v[244:247], v18 offset:6240
	v_readlane_b32 s8, v254, 38
	s_brev_b32 s9, 1
	s_movk_i32 s10, 0x2c0
	s_movk_i32 s11, 0x4100
	s_waitcnt vmcnt(15) lgkmcnt(3)
	v_pk_fma_f32 v[250:251], v[14:15], v[250:251], v[182:183]
	v_pk_fma_f32 v[248:249], v[204:205], v[248:249], v[180:181]
	global_store_dwordx4 v[26:27], v[248:251], off
	ds_read_b128 v[248:251], v18 offset:7280
	v_add_co_u32_e32 v26, vcc, s4, v16
	s_mov_b32 s4, 0x87000
	s_nop 0
	v_addc_co_u32_e32 v27, vcc, 0, v17, vcc
	s_waitcnt vmcnt(15) lgkmcnt(3)
	v_pk_fma_f32 v[238:239], v[14:15], v[238:239], v[178:179]
	v_pk_fma_f32 v[236:237], v[204:205], v[236:237], v[176:177]
	global_store_dwordx4 v[26:27], v[236:239], off offset:-4096
	ds_read_b128 v[236:239], v18 offset:8320
	s_movk_i32 s12, 0x41
	s_waitcnt vmcnt(15) lgkmcnt(3)
	v_pk_fma_f32 v[242:243], v[14:15], v[242:243], v[174:175]
	v_pk_fma_f32 v[240:241], v[204:205], v[240:241], v[172:173]
	global_store_dwordx4 v[26:27], v[240:243], off
	ds_read_b128 v[240:243], v18 offset:9360
	v_add_co_u32_e32 v26, vcc, s4, v16
	s_mov_b32 s4, 0x89000
	s_nop 0
	v_addc_co_u32_e32 v27, vcc, 0, v17, vcc
	s_waitcnt vmcnt(15) lgkmcnt(3)
	v_pk_fma_f32 v[246:247], v[14:15], v[246:247], v[170:171]
	v_pk_fma_f32 v[244:245], v[204:205], v[244:245], v[168:169]
	global_store_dwordx4 v[26:27], v[244:247], off offset:-4096
	ds_read_b128 v[244:247], v18 offset:10400
	s_waitcnt vmcnt(15) lgkmcnt(3)
	v_pk_fma_f32 v[250:251], v[14:15], v[250:251], v[166:167]
	v_pk_fma_f32 v[248:249], v[204:205], v[248:249], v[164:165]
	global_store_dwordx4 v[26:27], v[248:251], off
	ds_read_b128 v[248:251], v18 offset:11440
	v_add_co_u32_e32 v26, vcc, s4, v16
	s_mov_b32 s4, 0x8b000
	s_nop 0
	v_addc_co_u32_e32 v27, vcc, 0, v17, vcc
	s_waitcnt vmcnt(15) lgkmcnt(3)
	v_pk_fma_f32 v[238:239], v[14:15], v[238:239], v[162:163]
	v_pk_fma_f32 v[236:237], v[204:205], v[236:237], v[160:161]
	global_store_dwordx4 v[26:27], v[236:239], off offset:-4096
	ds_read_b128 v[236:239], v18 offset:12480
	s_waitcnt vmcnt(15) lgkmcnt(3)
	v_pk_fma_f32 v[242:243], v[14:15], v[242:243], v[158:159]
	v_pk_fma_f32 v[240:241], v[204:205], v[240:241], v[156:157]
	global_store_dwordx4 v[26:27], v[240:243], off
	ds_read_b128 v[240:243], v18 offset:13520
	v_add_co_u32_e32 v26, vcc, s4, v16
	s_mov_b32 s4, 0x8d000
	s_nop 0
	v_addc_co_u32_e32 v27, vcc, 0, v17, vcc
	s_waitcnt vmcnt(15) lgkmcnt(3)
	v_pk_fma_f32 v[246:247], v[14:15], v[246:247], v[154:155]
	v_pk_fma_f32 v[244:245], v[204:205], v[244:245], v[152:153]
	global_store_dwordx4 v[26:27], v[244:247], off offset:-4096
	ds_read_b128 v[244:247], v18 offset:14560
	s_waitcnt vmcnt(15) lgkmcnt(3)
	v_pk_fma_f32 v[250:251], v[14:15], v[250:251], v[150:151]
	v_pk_fma_f32 v[248:249], v[204:205], v[248:249], v[148:149]
	global_store_dwordx4 v[26:27], v[248:251], off
	v_add_co_u32_e32 v26, vcc, s4, v16
	s_waitcnt vmcnt(15) lgkmcnt(2)
	v_pk_fma_f32 v[238:239], v[14:15], v[238:239], v[146:147]
	v_pk_fma_f32 v[236:237], v[204:205], v[236:237], v[144:145]
	v_addc_co_u32_e32 v27, vcc, 0, v17, vcc
	global_store_dwordx4 v[26:27], v[236:239], off offset:-4096
	s_waitcnt vmcnt(15) lgkmcnt(1)
	v_pk_fma_f32 v[12:13], v[14:15], v[242:243], v[12:13]
	v_pk_fma_f32 v[10:11], v[204:205], v[240:241], v[10:11]
	global_store_dwordx4 v[26:27], v[10:13], off
	s_waitcnt vmcnt(15) lgkmcnt(0)
	v_pk_fma_f32 v[6:7], v[204:205], v[244:245], v[6:7]
	v_add_co_u32_e32 v10, vcc, s20, v16
	v_pk_fma_f32 v[8:9], v[14:15], v[246:247], v[8:9]
	s_nop 0
	v_addc_co_u32_e32 v11, vcc, 0, v17, vcc
	global_store_dwordx4 v[10:11], v[6:9], off
	s_nop 1
	v_or_b32_e32 v6, 15, v20
	v_mad_u64_u32 v[6:7], s[20:21], v6, s36, v[0:1]
	ds_read_b128 v[6:9], v6
	s_cselect_b64 s[20:21], -1, 0
	s_and_b64 s[20:21], s[20:21], s[58:59]
	s_and_b64 s[20:21], s[20:21], s[54:55]
	s_waitcnt vmcnt(15) lgkmcnt(0)
	v_pk_fma_f32 v[2:3], v[204:205], v[6:7], v[2:3]
	v_add_co_u32_e32 v6, vcc, 0x8f000, v16
	v_pk_fma_f32 v[4:5], v[14:15], v[8:9], v[4:5]
	s_nop 0
	v_addc_co_u32_e32 v7, vcc, 0, v17, vcc
	global_store_dwordx4 v[6:7], v[2:5], off
	s_barrier
	s_waitcnt vmcnt(0)
	s_andn2_b64 vcc, exec, s[20:21]
	s_cbranch_vccnz .LBB0_90
	s_add_u32 s20, s53, s86
	s_addc_u32 s21, s66, s87
	s_load_dwordx2 s[60:61], s[20:21], 0x614
	s_mov_b32 s26, s85
	s_waitcnt lgkmcnt(0)
	s_add_i32 s20, s60, s88
	s_cmp_lt_i32 s20, s61
	s_cselect_b64 s[22:23], -1, 0
	s_and_b64 s[22:23], s[56:57], s[22:23]
	s_andn2_b64 vcc, exec, s[22:23]
	s_cbranch_vccz .LBB0_141
	s_branch .LBB0_90

.LBB0_502:
	s_load_dwordx2 s[22:23], s[22:23], 0x0
	s_ashr_i32 s21, s20, 31
	s_lshl_b64 s[20:21], s[20:21], 12
	v_mov_b32_e32 v201, v200
	v_pk_mul_f32 v[14:15], v[200:201], v[198:199]
	s_waitcnt lgkmcnt(0)
	s_add_u32 s20, s22, s20
	s_addc_u32 s21, s23, s21
	v_ashrrev_i32_e32 v201, 2, v204
	s_add_u32 s20, s20, s44
	v_lshlrev_b32_e32 v0, 4, v0
	v_and_b32_e32 v204, -16, v201
	s_addc_u32 s21, s21, s45
	v_and_b32_e32 v0, 0x3f0, v0
	v_ashrrev_i32_e32 v205, 31, v204
	v_lshl_add_u64 v[198:199], s[20:21], 0, v[0:1]
	v_lshlrev_b64 v[208:209], 12, v[204:205]
	v_mad_u64_u32 v[204:205], s[20:21], v204, s36, v[0:1]
	v_lshl_add_u64 v[198:199], v[198:199], 0, v[208:209]
	ds_read_b128 v[236:239], v204
	ds_read_b128 v[240:243], v204 offset:1040
	ds_read_b128 v[244:247], v204 offset:2080
	ds_read_b128 v[248:251], v204 offset:3120
	v_pk_mul_f32 v[196:197], v[202:203], v[196:197]
	s_movk_i32 s4, 0x4000
	s_waitcnt lgkmcnt(3)
	v_pk_fma_f32 v[194:195], v[14:15], v[238:239], v[194:195]
	v_pk_fma_f32 v[192:193], v[196:197], v[236:237], v[192:193]
	global_store_dwordx4 v[198:199], v[192:195], off
	ds_read_b128 v[236:239], v204 offset:4160
	s_waitcnt lgkmcnt(3)
	v_pk_fma_f32 v[188:189], v[196:197], v[240:241], v[188:189]
	v_add_co_u32_e32 v192, vcc, s92, v198
	v_pk_fma_f32 v[190:191], v[14:15], v[242:243], v[190:191]
	s_nop 0
	v_addc_co_u32_e32 v193, vcc, 0, v199, vcc
	global_store_dwordx4 v[192:193], v[188:191], off offset:-4096
	ds_read_b128 v[240:243], v204 offset:5200
	s_waitcnt lgkmcnt(3)
	v_pk_fma_f32 v[186:187], v[14:15], v[246:247], v[186:187]
	v_pk_fma_f32 v[184:185], v[196:197], v[244:245], v[184:185]
	global_store_dwordx4 v[192:193], v[184:187], off
	ds_read_b128 v[244:247], v204 offset:6240
	s_waitcnt lgkmcnt(3)
	v_pk_fma_f32 v[180:181], v[196:197], v[248:249], v[180:181]
	v_add_co_u32_e32 v184, vcc, s4, v198
	v_pk_fma_f32 v[182:183], v[14:15], v[250:251], v[182:183]
	s_nop 0
	v_addc_co_u32_e32 v185, vcc, 0, v199, vcc
	global_store_dwordx4 v[184:185], v[180:183], off offset:-4096
	ds_read_b128 v[248:251], v204 offset:7280
	s_mov_b32 s4, 0x8000
	s_waitcnt lgkmcnt(3)
	v_pk_fma_f32 v[178:179], v[14:15], v[238:239], v[178:179]
	v_pk_fma_f32 v[176:177], v[196:197], v[236:237], v[176:177]
	global_store_dwordx4 v[184:185], v[176:179], off
	ds_read_b128 v[236:239], v204 offset:8320
	s_waitcnt vmcnt(0) lgkmcnt(3)
	v_pk_fma_f32 v[172:173], v[196:197], v[240:241], v[172:173]
	v_add_co_u32_e32 v176, vcc, s37, v198
	v_pk_fma_f32 v[174:175], v[14:15], v[242:243], v[174:175]
	s_nop 0
	v_addc_co_u32_e32 v177, vcc, 0, v199, vcc
	global_store_dwordx4 v[176:177], v[172:175], off offset:-4096
	ds_read_b128 v[240:243], v204 offset:9360
	s_waitcnt lgkmcnt(3)
	v_pk_fma_f32 v[170:171], v[14:15], v[246:247], v[170:171]
	v_pk_fma_f32 v[168:169], v[196:197], v[244:245], v[168:169]
	global_store_dwordx4 v[176:177], v[168:171], off
	ds_read_b128 v[244:247], v204 offset:10400
	s_waitcnt lgkmcnt(3)
	v_pk_fma_f32 v[164:165], v[196:197], v[248:249], v[164:165]
	v_add_co_u32_e32 v168, vcc, s4, v198
	v_pk_fma_f32 v[166:167], v[14:15], v[250:251], v[166:167]
	s_nop 0
	v_addc_co_u32_e32 v169, vcc, 0, v199, vcc
	global_store_dwordx4 v[168:169], v[164:167], off offset:-4096
	ds_read_b128 v[248:251], v204 offset:11440
	s_mov_b32 s4, 0xa000
	s_waitcnt lgkmcnt(3)
	v_pk_fma_f32 v[162:163], v[14:15], v[238:239], v[162:163]
	v_pk_fma_f32 v[160:161], v[196:197], v[236:237], v[160:161]
	global_store_dwordx4 v[168:169], v[160:163], off
	ds_read_b128 v[236:239], v204 offset:12480
	s_waitcnt lgkmcnt(3)
	v_pk_fma_f32 v[156:157], v[196:197], v[240:241], v[156:157]
	v_add_co_u32_e32 v160, vcc, s4, v198
	v_pk_fma_f32 v[158:159], v[14:15], v[242:243], v[158:159]
	s_nop 0
	v_addc_co_u32_e32 v161, vcc, 0, v199, vcc
	global_store_dwordx4 v[160:161], v[156:159], off offset:-4096
	ds_read_b128 v[240:243], v204 offset:13520
	s_mov_b32 s4, 0xe000
	s_waitcnt lgkmcnt(3)
	v_pk_fma_f32 v[154:155], v[14:15], v[246:247], v[154:155]
	v_pk_fma_f32 v[152:153], v[196:197], v[244:245], v[152:153]
	global_store_dwordx4 v[160:161], v[152:155], off
	ds_read_b128 v[244:247], v204 offset:14560
	s_waitcnt lgkmcnt(3)
	v_pk_fma_f32 v[148:149], v[196:197], v[248:249], v[148:149]
	v_add_co_u32_e32 v152, vcc, s39, v198
	v_pk_fma_f32 v[150:151], v[14:15], v[250:251], v[150:151]
	s_nop 0
	v_addc_co_u32_e32 v153, vcc, 0, v199, vcc
	global_store_dwordx4 v[152:153], v[148:151], off offset:-4096
	s_waitcnt lgkmcnt(2)
	v_pk_fma_f32 v[146:147], v[14:15], v[238:239], v[146:147]
	v_pk_fma_f32 v[144:145], v[196:197], v[236:237], v[144:145]
	global_store_dwordx4 v[152:153], v[144:147], off
	s_waitcnt lgkmcnt(1)
	v_pk_fma_f32 v[10:11], v[196:197], v[240:241], v[10:11]
	v_add_co_u32_e32 v144, vcc, s4, v198
	v_pk_fma_f32 v[12:13], v[14:15], v[242:243], v[12:13]
	s_nop 0
	v_addc_co_u32_e32 v145, vcc, 0, v199, vcc
	global_store_dwordx4 v[144:145], v[10:13], off offset:-4096
	s_mov_b32 s4, 0xf000
	s_waitcnt lgkmcnt(0)
	v_pk_fma_f32 v[8:9], v[14:15], v[246:247], v[8:9]
	v_pk_fma_f32 v[6:7], v[196:197], v[244:245], v[6:7]
	global_store_dwordx4 v[144:145], v[6:9], off
	s_nop 1
	v_or_b32_e32 v6, 15, v201
	v_mad_u64_u32 v[6:7], s[20:21], v6, s36, v[0:1]
	ds_read_b128 v[6:9], v6
	v_mov_b32_e32 v0, v206
	s_mov_b32 s20, 0x80000
	s_waitcnt lgkmcnt(0)
	v_pk_fma_f32 v[2:3], v[196:197], v[6:7], v[2:3]
	v_add_co_u32_e32 v6, vcc, s4, v198
	v_pk_fma_f32 v[4:5], v[14:15], v[8:9], v[4:5]
	s_nop 0
	v_addc_co_u32_e32 v7, vcc, 0, v199, vcc
	global_store_dwordx4 v[6:7], v[2:5], off
	s_mov_b32 s4, 0x81000
	v_lshlrev_b32_e32 v0, 4, v0
	v_mov_b32_e32 v4, v206
	v_and_b32_e32 v0, 0x3f0, v0
	v_lshl_add_u64 v[2:3], s[30:31], 0, v[0:1]
	v_ashrrev_i32_e32 v0, 2, v4
	v_and_b32_e32 v4, -16, v0
	v_ashrrev_i32_e32 v5, 31, v4
	v_lshlrev_b64 v[4:5], 12, v[4:5]
	v_lshl_add_u64 v[2:3], v[2:3], 0, v[4:5]
	v_add_co_u32_e32 v4, vcc, s20, v2
	s_mov_b32 s20, 0x82000
	s_nop 0
	v_addc_co_u32_e32 v5, vcc, 0, v3, vcc
	flat_load_dwordx4 v[192:195], v[4:5]
	v_add_co_u32_e32 v4, vcc, s4, v2
	s_mov_b32 s4, 0x83000
	s_nop 0
	v_addc_co_u32_e32 v5, vcc, 0, v3, vcc
	flat_load_dwordx4 v[188:191], v[4:5]
	v_add_co_u32_e32 v4, vcc, s20, v2
	s_mov_b32 s20, 0x84000
	s_nop 0
	v_addc_co_u32_e32 v5, vcc, 0, v3, vcc
	flat_load_dwordx4 v[184:187], v[4:5]
	v_add_co_u32_e32 v4, vcc, s4, v2
	s_mov_b32 s4, 0x85000
	s_nop 0
	v_addc_co_u32_e32 v5, vcc, 0, v3, vcc
	flat_load_dwordx4 v[180:183], v[4:5]
	v_add_co_u32_e32 v4, vcc, s20, v2
	s_mov_b32 s20, 0x86000
	s_nop 0
	v_addc_co_u32_e32 v5, vcc, 0, v3, vcc
	flat_load_dwordx4 v[176:179], v[4:5]
	v_add_co_u32_e32 v4, vcc, s4, v2
	s_mov_b32 s4, 0x87000
	s_nop 0
	v_addc_co_u32_e32 v5, vcc, 0, v3, vcc
	flat_load_dwordx4 v[172:175], v[4:5]
	v_add_co_u32_e32 v4, vcc, s20, v2
	s_mov_b32 s20, 0x88000
	s_nop 0
	v_addc_co_u32_e32 v5, vcc, 0, v3, vcc
	flat_load_dwordx4 v[168:171], v[4:5]
	v_add_co_u32_e32 v4, vcc, s4, v2
	s_mov_b32 s4, 0x89000
	s_nop 0
	v_addc_co_u32_e32 v5, vcc, 0, v3, vcc
	flat_load_dwordx4 v[164:167], v[4:5]
	v_add_co_u32_e32 v4, vcc, s20, v2
	s_mov_b32 s20, 0x8a000
	s_nop 0
	v_addc_co_u32_e32 v5, vcc, 0, v3, vcc
	flat_load_dwordx4 v[160:163], v[4:5]
	v_add_co_u32_e32 v4, vcc, s4, v2
	s_mov_b32 s4, 0x8b000
	s_nop 0
	v_addc_co_u32_e32 v5, vcc, 0, v3, vcc
	flat_load_dwordx4 v[156:159], v[4:5]
	v_add_co_u32_e32 v4, vcc, s20, v2
	s_mov_b32 s20, 0x8c000
	s_nop 0
	v_addc_co_u32_e32 v5, vcc, 0, v3, vcc
	flat_load_dwordx4 v[152:155], v[4:5]
	v_add_co_u32_e32 v4, vcc, s4, v2
	s_mov_b32 s4, 0x8d000
	s_nop 0
	v_addc_co_u32_e32 v5, vcc, 0, v3, vcc
	flat_load_dwordx4 v[148:151], v[4:5]
	v_add_co_u32_e32 v4, vcc, s20, v2
	s_nop 1
	v_addc_co_u32_e32 v5, vcc, 0, v3, vcc
	flat_load_dwordx4 v[144:147], v[4:5]
	v_add_co_u32_e32 v4, vcc, s4, v2
	s_nop 1
	v_addc_co_u32_e32 v5, vcc, 0, v3, vcc
	flat_load_dwordx4 v[10:13], v[4:5]
	v_add_co_u32_e32 v4, vcc, 0x8e000, v2
	s_nop 1
	v_addc_co_u32_e32 v5, vcc, 0, v3, vcc
	v_add_co_u32_e32 v2, vcc, 0x8f000, v2
	flat_load_dwordx4 v[6:9], v[4:5]
	s_nop 0
	v_addc_co_u32_e32 v3, vcc, 0, v3, vcc
	flat_load_dwordx4 v[2:5], v[2:3]
	s_waitcnt lgkmcnt(0)
	s_barrier
	s_and_saveexec_b64 s[20:21], s[40:41]
	s_cbranch_execz .LBB0_504
	v_lshlrev_b32_e32 v0, 2, v230
	v_lshl_add_u32 v198, v231, 2, v0
	ds_write2_b32 v198, v128, v112 offset1:32
	v_add_u32_e32 v112, 0x400, v198
	ds_write2_b32 v112, v129, v113 offset0:4 offset1:36
	v_add_u32_e32 v112, 0x800, v198
	ds_write2_b32 v112, v130, v114 offset0:8 offset1:40
	v_add_u32_e32 v112, 0xc00, v198
	ds_write2_b32 v112, v131, v115 offset0:12 offset1:44
	v_add_u32_e32 v112, 0x2000, v198
	ds_write2_b32 v112, v132, v116 offset0:32 offset1:64
	v_add_u32_e32 v112, 0x2400, v198
	ds_write2_b32 v112, v133, v117 offset0:36 offset1:68
	v_add_u32_e32 v112, 0x2800, v198
	ds_write2_b32 v112, v134, v118 offset0:40 offset1:72
	v_add_u32_e32 v112, 0x2c00, v198
	ds_write2_b32 v112, v135, v119 offset0:44 offset1:76
	v_add_u32_e32 v112, 0x4000, v198
	ds_write2_b32 v112, v136, v120 offset0:64 offset1:96
	v_add_u32_e32 v112, 0x4400, v198
	ds_write2_b32 v112, v137, v121 offset0:68 offset1:100
	v_add_u32_e32 v112, 0x4800, v198
	ds_write2_b32 v112, v138, v122 offset0:72 offset1:104
	v_add_u32_e32 v112, 0x4c00, v198
	ds_write2_b32 v112, v139, v123 offset0:76 offset1:108
	v_add_u32_e32 v112, 0x6000, v198
	ds_write2_b32 v112, v140, v124 offset0:96 offset1:128
	v_add_u32_e32 v112, 0x6400, v198
	ds_write2_b32 v112, v141, v125 offset0:100 offset1:132
	v_add_u32_e32 v112, 0x6800, v198
	ds_write2_b32 v112, v142, v126 offset0:104 offset1:136
	v_add_u32_e32 v112, 0x6c00, v198
	ds_write2_b32 v112, v143, v127 offset0:108 offset1:140
	v_add_u32_e32 v112, 0x8000, v198
	ds_write2_b32 v112, v96, v80 offset0:128 offset1:160
	v_add_u32_e32 v80, 0x8400, v198
	ds_write2_b32 v80, v97, v81 offset0:132 offset1:164
	v_add_u32_e32 v80, 0x8800, v198
	ds_write2_b32 v80, v98, v82 offset0:136 offset1:168
	v_add_u32_e32 v80, 0x8c00, v198
	ds_write2_b32 v80, v99, v83 offset0:140 offset1:172
	v_add_u32_e32 v80, 0xa000, v198
	ds_write2_b32 v80, v100, v84 offset0:160 offset1:192
	v_add_u32_e32 v80, 0xa400, v198
	ds_write2_b32 v80, v101, v85 offset0:164 offset1:196
	v_add_u32_e32 v80, 0xa800, v198
	ds_write2_b32 v80, v102, v86 offset0:168 offset1:200
	v_add_u32_e32 v80, 0xac00, v198
	ds_write2_b32 v80, v103, v87 offset0:172 offset1:204
	v_add_u32_e32 v80, 0xc000, v198
	ds_write2_b32 v80, v104, v88 offset0:192 offset1:224
	v_add_u32_e32 v80, 0xc400, v198
	ds_write2_b32 v80, v105, v89 offset0:196 offset1:228
	v_add_u32_e32 v80, 0xc800, v198
	ds_write2_b32 v80, v106, v90 offset0:200 offset1:232
	v_add_u32_e32 v80, 0xcc00, v198
	ds_write2_b32 v80, v107, v91 offset0:204 offset1:236
	v_add_u32_e32 v80, 0xe200, v198
	ds_write2_b32 v80, v108, v92 offset0:96 offset1:128
	v_add_u32_e32 v80, 0xe600, v198
	ds_write2_b32 v80, v109, v93 offset0:100 offset1:132
	v_add_u32_e32 v80, 0xea00, v198
	ds_write2_b32 v80, v110, v94 offset0:104 offset1:136
	v_add_u32_e32 v80, 0xee00, v198
	ds_write2_b32 v80, v111, v95 offset0:108 offset1:140
	v_add_u32_e32 v80, 0x10400, v198
	ds_write_b32 v80, v64
	v_add_u32_e32 v64, 0x10810, v198
	ds_write_b32 v64, v65
	v_add_u32_e32 v64, 0x10c20, v198
	ds_write_b32 v64, v66
	v_add_u32_e32 v64, 0x11030, v198
	ds_write_b32 v64, v67
	v_add_u32_e32 v64, 0x12480, v198
	ds_write_b32 v64, v68
	v_add_u32_e32 v64, 0x12890, v198
	ds_write_b32 v64, v69
	v_add_u32_e32 v64, 0x12ca0, v198
	ds_write_b32 v64, v70
	v_add_u32_e32 v64, 0x130b0, v198
	ds_write_b32 v64, v71
	v_add_u32_e32 v64, 0x14500, v198
	ds_write_b32 v64, v72
	v_add_u32_e32 v64, 0x14910, v198
	ds_write_b32 v64, v73
	v_add_u32_e32 v64, 0x14d20, v198
	ds_write_b32 v64, v74
	v_add_u32_e32 v64, 0x15130, v198
	ds_write_b32 v64, v75
	v_add_u32_e32 v64, 0x16580, v198
	ds_write_b32 v64, v76
	v_add_u32_e32 v64, 0x16990, v198
	ds_write_b32 v64, v77
	v_add_u32_e32 v64, 0x16da0, v198
	ds_write_b32 v64, v78
	v_add_u32_e32 v64, 0x171b0, v198
	ds_write_b32 v64, v79
	v_add_u32_e32 v64, 0x10480, v198
	ds_write_b32 v64, v48
	v_add_u32_e32 v48, 0x10890, v198
	ds_write_b32 v48, v49
	v_add_u32_e32 v48, 0x10ca0, v198
	ds_write_b32 v48, v50
	v_add_u32_e32 v48, 0x110b0, v198
	ds_write_b32 v48, v51
	v_add_u32_e32 v48, 0x12500, v198
	ds_write_b32 v48, v52
	v_add_u32_e32 v48, 0x12910, v198
	ds_write_b32 v48, v53
	v_add_u32_e32 v48, 0x12d20, v198
	ds_write_b32 v48, v54
	v_add_u32_e32 v48, 0x13130, v198
	ds_write_b32 v48, v55
	v_add_u32_e32 v48, 0x14580, v198
	ds_write_b32 v48, v56
	v_add_u32_e32 v48, 0x14990, v198
	ds_write_b32 v48, v57
	v_add_u32_e32 v48, 0x14da0, v198
	ds_write_b32 v48, v58
	v_add_u32_e32 v48, 0x151b0, v198
	ds_write_b32 v48, v59
	v_add_u32_e32 v48, 0x16600, v198
	ds_write_b32 v48, v60
	v_add_u32_e32 v48, 0x16a10, v198
	ds_write_b32 v48, v61
	v_add_u32_e32 v48, 0x16e20, v198
	ds_write_b32 v48, v62
	v_add_u32_e32 v48, 0x17230, v198
	ds_write_b32 v48, v63
	v_add_u32_e32 v48, 0x18600, v198
	ds_write_b32 v48, v32
	v_add_u32_e32 v32, 0x18a10, v198
	ds_write_b32 v32, v33
	v_add_u32_e32 v32, 0x18e20, v198
	ds_write_b32 v32, v34
	v_add_u32_e32 v32, 0x19230, v198
	ds_write_b32 v32, v35
	v_add_u32_e32 v32, 0x1a680, v198
	ds_write_b32 v32, v36
	v_add_u32_e32 v32, 0x1aa90, v198
	ds_write_b32 v32, v37
	v_add_u32_e32 v32, 0x1aea0, v198
	ds_write_b32 v32, v38
	v_add_u32_e32 v32, 0x1b2b0, v198
	ds_write_b32 v32, v39
	v_add_u32_e32 v32, 0x1c700, v198
	ds_write_b32 v32, v40
	v_add_u32_e32 v32, 0x1cb10, v198
	ds_write_b32 v32, v41
	v_add_u32_e32 v32, 0x1cf20, v198
	ds_write_b32 v32, v42
	v_add_u32_e32 v32, 0x1d330, v198
	ds_write_b32 v32, v43
	v_add_u32_e32 v32, 0x1e780, v198
	ds_write_b32 v32, v44
	v_add_u32_e32 v32, 0x1eb90, v198
	ds_write_b32 v32, v45
	v_add_u32_e32 v32, 0x1efa0, v198
	ds_write_b32 v32, v46
	v_mov_b32_e32 v32, 0x7b
	v_lshl_or_b32 v32, v229, 2, v32
	v_mad_u64_u32 v[32:33], s[22:23], v32, s36, v[0:1]
	v_add_u32_e32 v0, 0x18680, v198
	ds_write_b32 v32, v47
	ds_write_b32 v0, v16
	v_add_u32_e32 v0, 0x18a90, v198
	ds_write_b32 v0, v17
	v_add_u32_e32 v0, 0x18ea0, v198
	ds_write_b32 v0, v18
	v_add_u32_e32 v0, 0x192b0, v198
	ds_write_b32 v0, v19
	v_add_u32_e32 v0, 0x1a700, v198
	ds_write_b32 v0, v20
	v_add_u32_e32 v0, 0x1ab10, v198
	ds_write_b32 v0, v21
	v_add_u32_e32 v0, 0x1af20, v198
	ds_write_b32 v0, v22
	v_add_u32_e32 v0, 0x1b330, v198
	ds_write_b32 v0, v23
	v_add_u32_e32 v0, 0x1c780, v198
	ds_write_b32 v0, v24
	v_add_u32_e32 v0, 0x1cb90, v198
	ds_write_b32 v0, v25
	v_add_u32_e32 v0, 0x1cfa0, v198
	ds_write_b32 v0, v26
	v_add_u32_e32 v0, 0x1d3b0, v198
	ds_write_b32 v0, v27
	v_add_u32_e32 v0, 0x1e800, v198
	ds_write_b32 v0, v28
	v_add_u32_e32 v0, 0x1ec10, v198
	ds_write_b32 v0, v29
	v_add_u32_e32 v0, 0x1f020, v198
	ds_write_b32 v0, v30
	ds_write_b32 v32, v31 offset:128

.LBB0_508:
	s_load_dwordx2 s[22:23], s[22:23], 0x0
	s_ashr_i32 s21, s20, 31
	s_lshl_b64 s[20:21], s[20:21], 12
	v_ashrrev_i32_e32 v20, 2, v16
	v_lshlrev_b32_e32 v0, 4, v0
	s_waitcnt lgkmcnt(0)
	s_add_u32 s20, s22, s20
	s_addc_u32 s21, s23, s21
	s_add_u32 s20, s20, s44
	v_and_b32_e32 v22, -16, v20
	s_addc_u32 s21, s21, s45
	v_and_b32_e32 v0, 0x3f0, v0
	v_ashrrev_i32_e32 v23, 31, v22
	v_lshl_add_u64 v[18:19], s[20:21], 0, v[0:1]
	v_lshlrev_b64 v[16:17], 12, v[22:23]
	v_lshl_add_u64 v[16:17], v[18:19], 0, v[16:17]
	v_mad_u64_u32 v[18:19], s[20:21], v22, s36, v[0:1]
	ds_read_b128 v[236:239], v18
	ds_read_b128 v[240:243], v18 offset:1040
	ds_read_b128 v[244:247], v18 offset:2080
	ds_read_b128 v[248:251], v18 offset:3120
	s_mov_b32 s4, 0x81000
	v_add_co_u32_e32 v26, vcc, s4, v16
	s_mov_b32 s4, 0x83000
	s_waitcnt vmcnt(0) lgkmcnt(3)
	v_pk_fma_f32 v[238:239], v[14:15], v[238:239], v[194:195]
	v_pk_fma_f32 v[236:237], v[196:197], v[236:237], v[192:193]
	v_addc_co_u32_e32 v27, vcc, 0, v17, vcc
	global_store_dwordx4 v[26:27], v[236:239], off offset:-4096
	ds_read_b128 v[236:239], v18 offset:4160
	s_mov_b32 s20, 0x8f000
	s_cmp_lg_u32 s75, 0
	s_mov_b32 s27, s83
	s_movk_i32 s28, 0x60
	s_waitcnt lgkmcnt(3)
	v_pk_fma_f32 v[242:243], v[14:15], v[242:243], v[190:191]
	v_pk_fma_f32 v[240:241], v[196:197], v[240:241], v[188:189]
	global_store_dwordx4 v[26:27], v[240:243], off
	ds_read_b128 v[240:243], v18 offset:5200
	v_add_co_u32_e32 v26, vcc, s4, v16
	s_mov_b32 s4, 0x85000
	s_nop 0
	v_addc_co_u32_e32 v27, vcc, 0, v17, vcc
	s_waitcnt lgkmcnt(3)
	v_pk_fma_f32 v[246:247], v[14:15], v[246:247], v[186:187]
	v_pk_fma_f32 v[244:245], v[196:197], v[244:245], v[184:185]
	global_store_dwordx4 v[26:27], v[244:247], off offset:-4096
	ds_read_b128 v[244:247], v18 offset:6240
	s_mov_b32 s29, 0x2aaaaaab
	s_mov_b32 s30, 0x1800000
	s_waitcnt lgkmcnt(3)
	v_pk_fma_f32 v[250:251], v[14:15], v[250:251], v[182:183]
	v_pk_fma_f32 v[248:249], v[196:197], v[248:249], v[180:181]
	global_store_dwordx4 v[26:27], v[248:251], off
	ds_read_b128 v[248:251], v18 offset:7280
	v_add_co_u32_e32 v26, vcc, s4, v16
	s_mov_b32 s4, 0x87000
	s_nop 0
	v_addc_co_u32_e32 v27, vcc, 0, v17, vcc
	s_waitcnt lgkmcnt(3)
	v_pk_fma_f32 v[238:239], v[14:15], v[238:239], v[178:179]
	v_pk_fma_f32 v[236:237], v[196:197], v[236:237], v[176:177]
	global_store_dwordx4 v[26:27], v[236:239], off offset:-4096
	ds_read_b128 v[236:239], v18 offset:8320
	s_waitcnt lgkmcnt(3)
	v_pk_fma_f32 v[242:243], v[14:15], v[242:243], v[174:175]
	v_pk_fma_f32 v[240:241], v[196:197], v[240:241], v[172:173]
	global_store_dwordx4 v[26:27], v[240:243], off
	ds_read_b128 v[240:243], v18 offset:9360
	v_add_co_u32_e32 v26, vcc, s4, v16
	s_mov_b32 s4, 0x89000
	s_nop 0
	v_addc_co_u32_e32 v27, vcc, 0, v17, vcc
	s_waitcnt lgkmcnt(3)
	v_pk_fma_f32 v[246:247], v[14:15], v[246:247], v[170:171]
	v_pk_fma_f32 v[244:245], v[196:197], v[244:245], v[168:169]
	global_store_dwordx4 v[26:27], v[244:247], off offset:-4096
	ds_read_b128 v[244:247], v18 offset:10400
	s_waitcnt lgkmcnt(3)
	v_pk_fma_f32 v[250:251], v[14:15], v[250:251], v[166:167]
	v_pk_fma_f32 v[248:249], v[196:197], v[248:249], v[164:165]
	global_store_dwordx4 v[26:27], v[248:251], off
	ds_read_b128 v[248:251], v18 offset:11440
	v_add_co_u32_e32 v26, vcc, s4, v16
	s_mov_b32 s4, 0x8b000
	s_nop 0
	v_addc_co_u32_e32 v27, vcc, 0, v17, vcc
	s_waitcnt lgkmcnt(3)
	v_pk_fma_f32 v[238:239], v[14:15], v[238:239], v[162:163]
	v_pk_fma_f32 v[236:237], v[196:197], v[236:237], v[160:161]
	global_store_dwordx4 v[26:27], v[236:239], off offset:-4096
	ds_read_b128 v[236:239], v18 offset:12480
	s_waitcnt lgkmcnt(3)
	v_pk_fma_f32 v[242:243], v[14:15], v[242:243], v[158:159]
	v_pk_fma_f32 v[240:241], v[196:197], v[240:241], v[156:157]
	global_store_dwordx4 v[26:27], v[240:243], off
	ds_read_b128 v[240:243], v18 offset:13520
	v_add_co_u32_e32 v26, vcc, s4, v16
	s_mov_b32 s4, 0x8d000
	s_nop 0
	v_addc_co_u32_e32 v27, vcc, 0, v17, vcc
	s_waitcnt lgkmcnt(3)
	v_pk_fma_f32 v[246:247], v[14:15], v[246:247], v[154:155]
	v_pk_fma_f32 v[244:245], v[196:197], v[244:245], v[152:153]
	global_store_dwordx4 v[26:27], v[244:247], off offset:-4096
	ds_read_b128 v[244:247], v18 offset:14560
	s_waitcnt lgkmcnt(3)
	v_pk_fma_f32 v[250:251], v[14:15], v[250:251], v[150:151]
	v_pk_fma_f32 v[248:249], v[196:197], v[248:249], v[148:149]
	global_store_dwordx4 v[26:27], v[248:251], off
	v_add_co_u32_e32 v26, vcc, s4, v16
	s_waitcnt lgkmcnt(2)
	v_pk_fma_f32 v[238:239], v[14:15], v[238:239], v[146:147]
	v_pk_fma_f32 v[236:237], v[196:197], v[236:237], v[144:145]
	v_addc_co_u32_e32 v27, vcc, 0, v17, vcc
	global_store_dwordx4 v[26:27], v[236:239], off offset:-4096
	s_waitcnt lgkmcnt(1)
	v_pk_fma_f32 v[12:13], v[14:15], v[242:243], v[12:13]
	v_pk_fma_f32 v[10:11], v[196:197], v[240:241], v[10:11]
	global_store_dwordx4 v[26:27], v[10:13], off
	s_waitcnt lgkmcnt(0)
	v_pk_fma_f32 v[6:7], v[196:197], v[244:245], v[6:7]
	v_add_co_u32_e32 v10, vcc, s20, v16
	v_pk_fma_f32 v[8:9], v[14:15], v[246:247], v[8:9]
	s_nop 0
	v_addc_co_u32_e32 v11, vcc, 0, v17, vcc
	global_store_dwordx4 v[10:11], v[6:9], off offset:-4096
	s_nop 1
	v_or_b32_e32 v6, 15, v20
	v_mad_u64_u32 v[6:7], s[20:21], v6, s36, v[0:1]
	ds_read_b128 v[6:9], v6
	s_cselect_b64 s[20:21], -1, 0
	s_or_b64 s[20:21], s[20:21], s[66:67]
	s_or_b64 s[20:21], s[20:21], s[54:55]
	s_or_b64 s[20:21], s[20:21], s[56:57]
	s_waitcnt lgkmcnt(0)
	v_pk_fma_f32 v[4:5], v[14:15], v[8:9], v[4:5]
	v_pk_fma_f32 v[2:3], v[196:197], v[6:7], v[2:3]
	global_store_dwordx4 v[10:11], v[2:5], off
	s_barrier
	s_waitcnt vmcnt(0)
	s_or_b64 s[20:21], s[20:21], s[58:59]
	s_or_b64 s[20:21], s[20:21], s[60:61]
	s_and_b64 vcc, exec, s[20:21]
	s_movk_i32 s66, 0xff
	s_cbranch_vccnz .LBB0_453
